# edge trims: literal threshold compare (no s_mov) and first-half QK head K-fragment addresses computed before the barrier
# speedup vs baseline: 1.0044x; 1.0002x over previous
; __device__ __forceinline__ void finishSM(f32x16& p0, f32x16& p1, float alpha, float& l_reg, bf16x8& pa0, bf16x8& pa1, bf16x8& pa2, bf16x8& pa3) {
; #pragma unroll
;     for (int r = 0; r < 16; ++r) p1[r] = __builtin_amdgcn_exp2f(p1[r]);
;     float ps = 0;
; #pragma unroll
;     for (int r = 0; r < 16; ++r) ps += p0[r];
; #pragma unroll
;     for (int r = 0; r < 16; ++r) ps += p1[r];
;     { auto rr = __builtin_amdgcn_permlane32_swap(__float_as_uint(ps), __float_as_uint(ps), false, false);
;       ps = __uint_as_float(rr[0]) + __uint_as_float(rr[1]); }
;     l_reg = l_reg * alpha + ps;
;     ...
;     PK4(p0, 0, pa0); PK4(p0, 8, pa1); PK4(p1, 0, pa2); PK4(p1, 8, pa3);
;     ...
; }
; __device__ __forceinline__ void qkt(f32x16& p0, f32x16& p1, const char* Kn, const bf16x8* qr, int r32, int hi) {
;     const char* Kr = Kn + KR_OFF;
;     p0 = f32x16{}; p1 = f32x16{};
;     __builtin_amdgcn_s_setprio(1);
; #pragma unroll
;     for (int d0 = 0; d0 < 8; ++d0) { const int cb = (d0 * 16 + hi * 8) * 2;
;         const bf16x8 b0 = *reinterpret_cast<const bf16x8*>(Kn + KNSWZ(r32, cb));
;         const bf16x8 b1 = *reinterpret_cast<const bf16x8*>(Kn + KNSWZ(32 + r32, cb));
;         p0 = __builtin_amdgcn_mfma_f32_32x32x16_bf16(b0, qr[d0], p0, 0, 0, 0);
;         p1 = __builtin_amdgcn_mfma_f32_32x32x16_bf16(b1, qr[d0], p1, 0, 0, 0); }
; #pragma unroll
;     for (int d0 = 0; d0 < 4; ++d0) { const int cb = (d0 * 16 + hi * 8) * 2;
;         const bf16x8 b0 = *reinterpret_cast<const bf16x8*>(Kr + KRSWZ(r32, cb));
;         const bf16x8 b1 = *reinterpret_cast<const bf16x8*>(Kr + KRSWZ(32 + r32, cb));
;         p0 = __builtin_amdgcn_mfma_f32_32x32x16_bf16(b0, qr[8 + d0], p0, 0, 0, 0);
;         p1 = __builtin_amdgcn_mfma_f32_32x32x16_bf16(b1, qr[8 + d0], p1, 0, 0, 0); }
; }
.LBB0_216:
	s_mul_i32 s0, s9, 0x6000
	s_add_i32 s14, s0, 0
	s_lshl_b32 s13, s9, 14
	s_add_i32 s16, s14, s6
	s_add_i32 s17, s7, s13
	s_add_i32 s18, s14, s8
	s_mov_b32 s13, s10
	s_mov_b32 s10, s15
	s_mul_i32 s0, s13, 0x6000
	s_add_i32 s0, s0, 0
	s_setprio 1
	ds_read_b128 v[80:83], v84
	ds_read_b128 v[84:87], v84 offset:8192
	ds_read_b128 v[196:199], v168
	ds_read_b128 v[168:171], v168 offset:8192
	v_add_u32_e32 v184, s0, v218
	s_waitcnt lgkmcnt(0)
	v_mfma_f32_32x32x16_bf16 v[96:111], v[80:83], v[156:159], 0
	v_mfma_f32_32x32x16_bf16 v[80:95], v[84:87], v[156:159], 0
	v_mfma_f32_32x32x16_bf16 v[96:111], v[196:199], v[152:155], v[96:111]
	v_mfma_f32_32x32x16_bf16 v[80:95], v[168:171], v[152:155], v[80:95]
	ds_read_b128 v[168:171], v184
	ds_read_b128 v[196:199], v184 offset:8192
	v_add_u32_e32 v184, s0, v221
	s_mov_b32 m0, s16
	s_add_u32 s100, s72, 0x26500000
	s_addc_u32 s101, s73, 0
	global_load_lds_dwordx4 v178, s[100:101]
	s_waitcnt lgkmcnt(0)
	v_mfma_f32_32x32x16_bf16 v[96:111], v[168:171], v[148:151], v[96:111]
	v_mfma_f32_32x32x16_bf16 v[80:95], v[196:199], v[148:151], v[80:95]
	ds_read_b128 v[168:171], v184
	ds_read_b128 v[196:199], v184 offset:8192
	v_add_u32_e32 v184, s0, v222
	s_waitcnt lgkmcnt(0)
	v_mfma_f32_32x32x16_bf16 v[96:111], v[168:171], v[144:147], v[96:111]
	v_mfma_f32_32x32x16_bf16 v[80:95], v[196:199], v[144:147], v[80:95]
	ds_read_b128 v[168:171], v184
	ds_read_b128 v[196:199], v184 offset:8192
	v_add_u32_e32 v184, s0, v223
	s_add_i32 m0, s16, 0x400
	s_nop 0
	global_load_lds_dwordx4 v180, s[100:101]
	s_waitcnt lgkmcnt(0)
	v_mfma_f32_32x32x16_bf16 v[96:111], v[168:171], v[140:143], v[96:111]
	v_mfma_f32_32x32x16_bf16 v[80:95], v[196:199], v[140:143], v[80:95]
	ds_read_b128 v[168:171], v184
	ds_read_b128 v[196:199], v184 offset:8192
	v_add_u32_e32 v184, s0, v224
	v_exp_f32_e32 v233, v73
	s_waitcnt lgkmcnt(0)
	v_mfma_f32_32x32x16_bf16 v[96:111], v[168:171], v[136:139], v[96:111]
	v_mfma_f32_32x32x16_bf16 v[80:95], v[196:199], v[136:139], v[80:95]
	ds_read_b128 v[168:171], v184
	ds_read_b128 v[196:199], v184 offset:8192
	v_add_u32_e32 v184, s0, v225
	s_mov_b32 m0, s17
	s_add_u32 s100, s72, 0x26500100
	s_addc_u32 s101, s73, 0
	global_load_lds_dwordx4 v176, s[100:101]
	v_exp_f32_e32 v250, v74
	s_waitcnt lgkmcnt(0)
	v_mfma_f32_32x32x16_bf16 v[96:111], v[168:171], v[132:135], v[96:111]
	v_mfma_f32_32x32x16_bf16 v[80:95], v[196:199], v[132:135], v[80:95]
	ds_read_b128 v[168:171], v184
	ds_read_b128 v[196:199], v184 offset:8192
	v_add_u32_e32 v184, s0, v226
	v_exp_f32_e32 v200, v75
	s_waitcnt lgkmcnt(0)
	v_mfma_f32_32x32x16_bf16 v[96:111], v[168:171], v[128:131], v[96:111]
	v_mfma_f32_32x32x16_bf16 v[80:95], v[196:199], v[128:131], v[80:95]
	ds_read_b128 v[168:171], v184 offset:16384
	ds_read_b128 v[196:199], v184 offset:20480
	v_add_u32_e32 v184, s0, v227
	s_add_i32 m0, s17, 0x400
	s_add_u32 s100, s72, 0x26500180
	s_addc_u32 s101, s73, 0
	global_load_lds_dwordx4 v176, s[100:101]
	v_exp_f32_e32 v195, v76
	s_waitcnt lgkmcnt(0)
	v_mfma_f32_32x32x16_bf16 v[96:111], v[168:171], v[124:127], v[96:111]
	v_mfma_f32_32x32x16_bf16 v[80:95], v[196:199], v[124:127], v[80:95]
	ds_read_b128 v[168:171], v184 offset:16384
	ds_read_b128 v[196:199], v184 offset:20480
	v_add_u32_e32 v184, s0, v228
	v_exp_f32_e32 v172, v77
	s_waitcnt lgkmcnt(0)
	v_mfma_f32_32x32x16_bf16 v[96:111], v[168:171], v[120:123], v[96:111]
	v_mfma_f32_32x32x16_bf16 v[80:95], v[196:199], v[120:123], v[80:95]
	ds_read_b128 v[168:171], v184 offset:16384
	ds_read_b128 v[196:199], v184 offset:20480
	v_add_u32_e32 v184, s0, v229
	s_add_i32 m0, s18, 0x4000
	s_add_u32 s100, s72, 0x21204000
	s_addc_u32 s101, s73, 0
	global_load_lds_dwordx4 v174, s[100:101]
	v_exp_f32_e32 v173, v78
	s_waitcnt lgkmcnt(0)
	v_mfma_f32_32x32x16_bf16 v[96:111], v[168:171], v[116:119], v[96:111]
	v_mfma_f32_32x32x16_bf16 v[80:95], v[196:199], v[116:119], v[80:95]
	ds_read_b128 v[168:171], v184 offset:16384
	ds_read_b128 v[196:199], v184 offset:20480
	v_exp_f32_e32 v184, v68
	v_exp_f32_e32 v79, v79
	s_waitcnt lgkmcnt(0)
	v_mfma_f32_32x32x16_bf16 v[96:111], v[168:171], v[112:115], v[96:111]
	v_exp_f32_e32 v168, v64
	v_add_f32_e32 v64, 0, v247
	v_add_f32_e32 v64, v249, v64
	v_add_f32_e32 v64, v245, v64
	v_add_f32_e32 v64, v248, v64
	v_add_f32_e32 v64, v244, v64
	v_add_f32_e32 v64, v246, v64
	v_add_f32_e32 v64, v242, v64
	v_add_f32_e32 v64, v243, v64
	v_add_f32_e32 v64, v239, v64
	v_add_f32_e32 v64, v241, v64
	v_add_f32_e32 v64, v238, v64
	v_add_f32_e32 v64, v240, v64
	v_add_f32_e32 v64, v235, v64
	v_exp_f32_e32 v169, v65
	v_add_f32_e32 v64, v237, v64
	v_exp_f32_e32 v170, v66
	v_add_f32_e32 v64, v234, v64
	v_exp_f32_e32 v171, v67
	v_add_f32_e32 v64, v236, v64
	v_add_f32_e32 v64, v168, v64
	v_mfma_f32_32x32x16_bf16 v[80:95], v[196:199], v[112:115], v[80:95]
	v_exp_f32_e32 v196, v69
	v_add_f32_e32 v64, v169, v64
	v_exp_f32_e32 v197, v70
	v_add_f32_e32 v64, v170, v64
	v_exp_f32_e32 v198, v71
	v_add_f32_e32 v64, v171, v64
	v_exp_f32_e32 v199, v72
	v_add_f32_e32 v64, v184, v64
	v_add_f32_e32 v64, v196, v64
	v_add_f32_e32 v64, v197, v64
	v_add_f32_e32 v64, v198, v64
	v_add_f32_e32 v64, v199, v64
	v_add_f32_e32 v64, v233, v64
	v_add_f32_e32 v64, v250, v64
	v_add_f32_e32 v64, v200, v64
	v_add_f32_e32 v64, v195, v64
	v_add_f32_e32 v64, v172, v64
	v_add_f32_e32 v64, v173, v64
	v_add_f32_e32 v231, v79, v64
	v_mov_b32_e32 v232, v231
	v_cvt_pk_bf16_f32 v64, v247, v249
	v_cvt_pk_bf16_f32 v65, v245, v248
	v_cvt_pk_bf16_f32 v66, v244, v246
	s_nop 1
	v_permlane32_swap_b32_e32 v231, v232
	v_cvt_pk_bf16_f32 v67, v242, v243
	v_permlane32_swap_b32_e32 v64, v66
	v_cvt_pk_bf16_f32 v68, v239, v241
	v_cvt_pk_bf16_f32 v69, v238, v240
	v_cvt_pk_bf16_f32 v70, v235, v237
	v_cvt_pk_bf16_f32 v71, v234, v236
	v_cvt_pk_bf16_f32 v72, v168, v169
	v_cvt_pk_bf16_f32 v73, v170, v171
	v_cvt_pk_bf16_f32 v74, v184, v196
	v_cvt_pk_bf16_f32 v75, v197, v198
	v_cvt_pk_bf16_f32 v76, v199, v233
	v_cvt_pk_bf16_f32 v77, v250, v200
	v_cvt_pk_bf16_f32 v78, v195, v172
	v_cvt_pk_bf16_f32 v79, v173, v79
	s_lshl_b32 s15, s15, 14
	v_add_u32_e32 v172, s15, v205
	ds_read_b64_tr_b16 v[168:169], v172 offset:0
	ds_read_b64_tr_b16 v[170:171], v172 offset:0x800
	ds_read_b64_tr_b16 v[196:197], v172 offset:0x1000
	ds_read_b64_tr_b16 v[198:199], v172 offset:0x1800
	ds_read_b64_tr_b16 v[234:235], v172 offset:0x2000
	ds_read_b64_tr_b16 v[236:237], v172 offset:0x2800
	ds_read_b64_tr_b16 v[238:239], v172 offset:0x3000
	ds_read_b64_tr_b16 v[240:241], v172 offset:0x3800
	v_permlane32_swap_b32_e32 v65, v67
	v_permlane32_swap_b32_e32 v68, v70
	v_permlane32_swap_b32_e32 v69, v71
	v_permlane32_swap_b32_e32 v72, v74
	v_permlane32_swap_b32_e32 v73, v75
	v_permlane32_swap_b32_e32 v76, v78
	v_permlane32_swap_b32_e32 v77, v79
	s_setprio 0
	s_waitcnt lgkmcnt(0)
; #define SBAR() __builtin_amdgcn_sched_barrier(0)
; __device__ __forceinline__ void qkt(f32x16& p0, f32x16& p1, const char* Kn, const bf16x8* qr, int r32, int hi) {
;     const char* Kr = Kn + KR_OFF;
;     p0 = f32x16{}; p1 = f32x16{};
;     __builtin_amdgcn_s_setprio(1);
; #pragma unroll
;     for (int d0 = 0; d0 < 8; ++d0) { const int cb = (d0 * 16 + hi * 8) * 2;
;         const bf16x8 b0 = *reinterpret_cast<const bf16x8*>(Kn + KNSWZ(r32, cb));
;         const bf16x8 b1 = *reinterpret_cast<const bf16x8*>(Kn + KNSWZ(32 + r32, cb));
;         p0 = __builtin_amdgcn_mfma_f32_32x32x16_bf16(b0, qr[d0], p0, 0, 0, 0);
;         p1 = __builtin_amdgcn_mfma_f32_32x32x16_bf16(b1, qr[d0], p1, 0, 0, 0); }
; #pragma unroll
;     for (int d0 = 0; d0 < 4; ++d0) { const int cb = (d0 * 16 + hi * 8) * 2;
;         const bf16x8 b0 = *reinterpret_cast<const bf16x8*>(Kr + KRSWZ(r32, cb));
;         const bf16x8 b1 = *reinterpret_cast<const bf16x8*>(Kr + KRSWZ(32 + r32, cb));
;         p0 = __builtin_amdgcn_mfma_f32_32x32x16_bf16(b0, qr[8 + d0], p0, 0, 0, 0);
;         p1 = __builtin_amdgcn_mfma_f32_32x32x16_bf16(b1, qr[8 + d0], p1, 0, 0, 0); }
; }
; __device__ __forceinline__ int v_st(int k, int c) { const int kk = (k & ~0xC) | ((k & 4) << 1) | ((k & 8) >> 1); return ((kk >> 3) * 4 + (c >> 5)) * 512 + ((kk & 7) * 32 + (c & 31)) * 2; }
; __device__ __forceinline__ int v_rd_base(int lane) { return ((lane & 3) << 3) | (((lane >> 2) & 3) << 6) | (((lane >> 4) & 1) << 5) | (((lane >> 5) & 1) << 8); }
; template <int OFF> __device__ __forceinline__ s16x4 tr_read(int vb) {
;     s16x4 r; asm volatile("ds_read_b64_tr_b16 %0, %1 offset:%2" : "=&v"(r) : "v"(vb), "i"(OFF) : "memory"); return r;
; }
; template <int D0> __device__ __forceinline__ void pv_one(f32x16& od, int vb, bf16x8 pa0, bf16x8 pa1, bf16x8 pa2, bf16x8 pa3) {
;     const s16x4 l0 = tr_read<v_rd_off(D0, 0, 0)>(vb), h0 = tr_read<v_rd_off(D0, 0, 1)>(vb), l1 = tr_read<v_rd_off(D0, 1, 0)>(vb), h1 = tr_read<v_rd_off(D0, 1, 1)>(vb);
;     const s16x4 l2 = tr_read<v_rd_off(D0, 2, 0)>(vb), h2 = tr_read<v_rd_off(D0, 2, 1)>(vb), l3 = tr_read<v_rd_off(D0, 3, 0)>(vb), h3 = tr_read<v_rd_off(D0, 3, 1)>(vb);
;     asm volatile("s_waitcnt lgkmcnt(0)" ::: "memory"); SBAR();
;     ...
;     od = __builtin_amdgcn_mfma_f32_32x32x16_bf16(pa0, PK(l0, h0), od, 0, 0, 0);
;     od = __builtin_amdgcn_mfma_f32_32x32x16_bf16(pa1, PK(l1, h1), od, 0, 0, 0);
	s_nop 0
	v_mfma_f32_32x32x16_bf16 v[0:15], v[64:67], v[168:171], v[0:15]
	ds_read_b64_tr_b16 v[168:169], v172 offset:0x200
	ds_read_b64_tr_b16 v[170:171], v172 offset:0xa00
	v_mfma_f32_32x32x16_bf16 v[0:15], v[68:71], v[196:199], v[0:15]
	ds_read_b64_tr_b16 v[196:197], v172 offset:0x1200
	ds_read_b64_tr_b16 v[198:199], v172 offset:0x1a00
	v_mfma_f32_32x32x16_bf16 v[0:15], v[72:75], v[234:237], v[0:15]
	ds_read_b64_tr_b16 v[234:235], v172 offset:0x2200
	ds_read_b64_tr_b16 v[236:237], v172 offset:0x2a00
	v_mfma_f32_32x32x16_bf16 v[0:15], v[76:79], v[238:241], v[0:15]
	ds_read_b64_tr_b16 v[238:239], v172 offset:0x3200
	ds_read_b64_tr_b16 v[240:241], v172 offset:0x3a00
	s_waitcnt lgkmcnt(0)
	v_mfma_f32_32x32x16_bf16 v[48:63], v[64:67], v[168:171], v[48:63]
	ds_read_b64_tr_b16 v[168:169], v172 offset:0x400
	ds_read_b64_tr_b16 v[170:171], v172 offset:0xc00
	v_mfma_f32_32x32x16_bf16 v[48:63], v[68:71], v[196:199], v[48:63]
	ds_read_b64_tr_b16 v[196:197], v172 offset:0x1400
	ds_read_b64_tr_b16 v[198:199], v172 offset:0x1c00
	v_mfma_f32_32x32x16_bf16 v[48:63], v[72:75], v[234:237], v[48:63]
	ds_read_b64_tr_b16 v[234:235], v172 offset:0x2400
	ds_read_b64_tr_b16 v[236:237], v172 offset:0x2c00
	v_mfma_f32_32x32x16_bf16 v[48:63], v[76:79], v[238:241], v[48:63]
	ds_read_b64_tr_b16 v[238:239], v172 offset:0x3400
	ds_read_b64_tr_b16 v[240:241], v172 offset:0x3c00
	s_waitcnt lgkmcnt(0)
	v_mfma_f32_32x32x16_bf16 v[32:47], v[64:67], v[168:171], v[32:47]
	ds_read_b64_tr_b16 v[168:169], v172 offset:0x600
	ds_read_b64_tr_b16 v[170:171], v172 offset:0xe00
	v_mfma_f32_32x32x16_bf16 v[32:47], v[68:71], v[196:199], v[32:47]
	ds_read_b64_tr_b16 v[196:197], v172 offset:0x1600
	ds_read_b64_tr_b16 v[198:199], v172 offset:0x1e00
	v_mfma_f32_32x32x16_bf16 v[32:47], v[72:75], v[234:237], v[32:47]
	ds_read_b64_tr_b16 v[234:235], v172 offset:0x2600
	ds_read_b64_tr_b16 v[236:237], v172 offset:0x2e00
	v_mfma_f32_32x32x16_bf16 v[32:47], v[76:79], v[238:241], v[32:47]
	ds_read_b64_tr_b16 v[238:239], v172 offset:0x3600
	ds_read_b64_tr_b16 v[240:241], v172 offset:0x3e00
	s_waitcnt lgkmcnt(0)
	v_mfma_f32_32x32x16_bf16 v[16:31], v[64:67], v[168:171], v[16:31]
	v_max_f32_e32 v64, v97, v97
	v_max_f32_e32 v65, v96, v96
	v_max_f32_e32 v64, v65, v64
	v_max3_f32 v64, v64, v98, v99
	v_max3_f32 v64, v64, v100, v101
	v_max3_f32 v64, v64, v102, v103
	v_max3_f32 v64, v64, v104, v105
	v_mfma_f32_32x32x16_bf16 v[16:31], v[68:71], v[196:199], v[16:31]
	v_max3_f32 v64, v64, v106, v107
	v_max3_f32 v64, v64, v108, v109
	v_max3_f32 v64, v64, v110, v111
	v_max3_f32 v64, v64, v80, v81
	v_max3_f32 v64, v64, v82, v83
	v_max3_f32 v64, v64, v84, v85
	v_max3_f32 v64, v64, v86, v87
	v_mfma_f32_32x32x16_bf16 v[16:31], v[72:75], v[234:237], v[16:31]
	v_max3_f32 v64, v64, v88, v89
	v_max3_f32 v64, v64, v90, v91
	v_max3_f32 v64, v64, v92, v93
	v_max3_f32 v64, v64, v94, v95
	v_mov_b32_e32 v65, v64
	s_nop 1
	v_permlane32_swap_b32_e32 v64, v65
	v_max_f32_e32 v65, v65, v65
	v_max_f32_e32 v64, v64, v64
	v_mfma_f32_32x32x16_bf16 v[16:31], v[76:79], v[238:241], v[16:31]
	v_max_f32_e32 v64, v64, v65
	v_sub_f32_e32 v65, v64, v182
	v_cmp_ge_f32_e32 vcc, 0x41300000, v65
	v_mov_b32_e32 v184, v182
	v_mov_b32_e32 v233, 1.0
	s_cmp_eq_u64 vcc, exec
	s_cbranch_scc0 .Latt_slow1
	s_cmp_lg_u32 s19, 0
	s_cbranch_scc0 .LBB0_228
.LBB0_221:
	v_exp_f32_e32 v182, v98
	v_exp_f32_e32 v172, v96
	v_exp_f32_e32 v173, v97
	v_exp_f32_e32 v195, v99
	v_exp_f32_e32 v196, v100
	v_exp_f32_e32 v197, v101
	v_exp_f32_e32 v198, v102
	v_exp_f32_e32 v199, v103
	v_exp_f32_e32 v200, v104
	v_exp_f32_e32 v234, v105
	v_exp_f32_e32 v235, v106
	v_exp_f32_e32 v236, v107
	v_exp_f32_e32 v237, v108
	v_exp_f32_e32 v238, v109
	v_exp_f32_e32 v239, v110
	v_exp_f32_e32 v240, v111
	v_add_u32_e32 v68, s14, v207
	v_add_u32_e32 v186, s14, v210
	s_mul_i32 s0, s10, 0x6000
	s_add_i32 s16, s0, 0
	s_add_i32 s17, s16, s6
	s_add_i32 s18, s16, s8
	s_waitcnt vmcnt(0) lgkmcnt(0)
	s_barrier
	s_add_i32 s15, s7, s15
	s_setprio 1
	ds_read_b128 v[64:67], v68
	ds_read_b128 v[68:71], v68 offset:8192
	ds_read_b128 v[168:171], v186
	ds_read_b128 v[186:189], v186 offset:8192
	s_waitcnt lgkmcnt(0)
	v_mfma_f32_32x32x16_bf16 v[96:111], v[64:67], v[156:159], 0
	v_mfma_f32_32x32x16_bf16 v[64:79], v[68:71], v[156:159], 0
	v_mfma_f32_32x32x16_bf16 v[96:111], v[168:171], v[152:155], v[96:111]
	v_mfma_f32_32x32x16_bf16 v[64:79], v[186:189], v[152:155], v[64:79]
	v_add_u32_e32 v186, s14, v218
	ds_read_b128 v[168:171], v186
	ds_read_b128 v[186:189], v186 offset:8192
	s_mov_b32 m0, s17
	s_add_u32 s100, s72, 0x26580000
	s_addc_u32 s101, s73, 0
	global_load_lds_dwordx4 v178, s[100:101]
	s_waitcnt lgkmcnt(0)
	v_mfma_f32_32x32x16_bf16 v[96:111], v[168:171], v[148:151], v[96:111]
	v_mfma_f32_32x32x16_bf16 v[64:79], v[186:189], v[148:151], v[64:79]
	v_add_u32_e32 v186, s14, v221
	ds_read_b128 v[168:171], v186
	ds_read_b128 v[186:189], v186 offset:8192
	s_waitcnt lgkmcnt(0)
	v_mfma_f32_32x32x16_bf16 v[96:111], v[168:171], v[144:147], v[96:111]
	v_mfma_f32_32x32x16_bf16 v[64:79], v[186:189], v[144:147], v[64:79]
	v_add_u32_e32 v186, s14, v222
	ds_read_b128 v[168:171], v186
	ds_read_b128 v[186:189], v186 offset:8192
	s_add_i32 m0, s17, 0x400
	s_nop 0
	global_load_lds_dwordx4 v180, s[100:101]
	v_exp_f32_e32 v190, v88
	s_waitcnt lgkmcnt(0)
	v_mfma_f32_32x32x16_bf16 v[96:111], v[168:171], v[140:143], v[96:111]
	v_mfma_f32_32x32x16_bf16 v[64:79], v[186:189], v[140:143], v[64:79]
	v_add_u32_e32 v186, s14, v223
	ds_read_b128 v[168:171], v186
	ds_read_b128 v[186:189], v186 offset:8192
	v_exp_f32_e32 v191, v89
	s_waitcnt lgkmcnt(0)
; __device__ __forceinline__ void finishSM(f32x16& p0, f32x16& p1, float alpha, float& l_reg, bf16x8& pa0, bf16x8& pa1, bf16x8& pa2, bf16x8& pa3) {
; #pragma unroll
;     for (int r = 0; r < 16; ++r) p1[r] = __builtin_amdgcn_exp2f(p1[r]);
;     float ps = 0;
; #pragma unroll
;     for (int r = 0; r < 16; ++r) ps += p0[r];
; #pragma unroll
;     for (int r = 0; r < 16; ++r) ps += p1[r];
;     { auto rr = __builtin_amdgcn_permlane32_swap(__float_as_uint(ps), __float_as_uint(ps), false, false);
;       ps = __uint_as_float(rr[0]) + __uint_as_float(rr[1]); }
;     l_reg = l_reg * alpha + ps;
;     ...
;     PK4(p0, 0, pa0); PK4(p0, 8, pa1); PK4(p1, 0, pa2); PK4(p1, 8, pa3);
;     ...
; }
; __device__ __forceinline__ void qkt(f32x16& p0, f32x16& p1, const char* Kn, const bf16x8* qr, int r32, int hi) {
;     const char* Kr = Kn + KR_OFF;
;     p0 = f32x16{}; p1 = f32x16{};
;     __builtin_amdgcn_s_setprio(1);
; #pragma unroll
;     for (int d0 = 0; d0 < 8; ++d0) { const int cb = (d0 * 16 + hi * 8) * 2;
;         const bf16x8 b0 = *reinterpret_cast<const bf16x8*>(Kn + KNSWZ(r32, cb));
;         const bf16x8 b1 = *reinterpret_cast<const bf16x8*>(Kn + KNSWZ(32 + r32, cb));
;         p0 = __builtin_amdgcn_mfma_f32_32x32x16_bf16(b0, qr[d0], p0, 0, 0, 0);
;         p1 = __builtin_amdgcn_mfma_f32_32x32x16_bf16(b1, qr[d0], p1, 0, 0, 0); }
; #pragma unroll
;     for (int d0 = 0; d0 < 4; ++d0) { const int cb = (d0 * 16 + hi * 8) * 2;
;         const bf16x8 b0 = *reinterpret_cast<const bf16x8*>(Kr + KRSWZ(r32, cb));
;         const bf16x8 b1 = *reinterpret_cast<const bf16x8*>(Kr + KRSWZ(32 + r32, cb));
;         p0 = __builtin_amdgcn_mfma_f32_32x32x16_bf16(b0, qr[8 + d0], p0, 0, 0, 0);
;         p1 = __builtin_amdgcn_mfma_f32_32x32x16_bf16(b1, qr[8 + d0], p1, 0, 0, 0); }
; }
	v_mfma_f32_32x32x16_bf16 v[96:111], v[168:171], v[136:139], v[96:111]
	v_mfma_f32_32x32x16_bf16 v[64:79], v[186:189], v[136:139], v[64:79]
	v_add_u32_e32 v186, s14, v224
	ds_read_b128 v[168:171], v186
	ds_read_b128 v[186:189], v186 offset:8192
	s_mov_b32 m0, s15
	s_add_u32 s100, s72, 0x26580100
	s_addc_u32 s101, s73, 0
	global_load_lds_dwordx4 v176, s[100:101]
	v_exp_f32_e32 v192, v90
	s_waitcnt lgkmcnt(0)
	v_mfma_f32_32x32x16_bf16 v[96:111], v[168:171], v[132:135], v[96:111]
	v_mfma_f32_32x32x16_bf16 v[64:79], v[186:189], v[132:135], v[64:79]
	v_add_u32_e32 v186, s14, v225
	ds_read_b128 v[168:171], v186
	ds_read_b128 v[186:189], v186 offset:8192
	v_exp_f32_e32 v193, v91
	s_waitcnt lgkmcnt(0)
	v_mfma_f32_32x32x16_bf16 v[96:111], v[168:171], v[128:131], v[96:111]
	v_mfma_f32_32x32x16_bf16 v[64:79], v[186:189], v[128:131], v[64:79]
	v_add_u32_e32 v186, s14, v226
	ds_read_b128 v[168:171], v186 offset:16384
	ds_read_b128 v[186:189], v186 offset:20480
	s_add_i32 m0, s15, 0x400
	s_add_u32 s100, s72, 0x26580180
	s_addc_u32 s101, s73, 0
	global_load_lds_dwordx4 v176, s[100:101]
	v_exp_f32_e32 v241, v92
	s_waitcnt lgkmcnt(0)
	v_mfma_f32_32x32x16_bf16 v[96:111], v[168:171], v[124:127], v[96:111]
	v_mfma_f32_32x32x16_bf16 v[64:79], v[186:189], v[124:127], v[64:79]
	v_add_u32_e32 v186, s14, v227
	ds_read_b128 v[168:171], v186 offset:16384
	ds_read_b128 v[186:189], v186 offset:20480
	v_exp_f32_e32 v242, v93
	s_waitcnt lgkmcnt(0)
	v_mfma_f32_32x32x16_bf16 v[96:111], v[168:171], v[120:123], v[96:111]
	v_mfma_f32_32x32x16_bf16 v[64:79], v[186:189], v[120:123], v[64:79]
	v_add_u32_e32 v186, s14, v228
	ds_read_b128 v[168:171], v186 offset:16384
	ds_read_b128 v[186:189], v186 offset:20480
	s_add_i32 m0, s18, 0x4000
	s_add_u32 s100, s72, 0x21206000
	s_addc_u32 s101, s73, 0
	global_load_lds_dwordx4 v174, s[100:101]
	v_exp_f32_e32 v94, v94
	s_waitcnt lgkmcnt(0)
	v_mfma_f32_32x32x16_bf16 v[96:111], v[168:171], v[116:119], v[96:111]
	v_mfma_f32_32x32x16_bf16 v[64:79], v[186:189], v[116:119], v[64:79]
	v_add_u32_e32 v186, s14, v229
	ds_read_b128 v[168:171], v186 offset:16384
	ds_read_b128 v[186:189], v186 offset:20480
	v_exp_f32_e32 v95, v95
	s_waitcnt lgkmcnt(0)
	v_mfma_f32_32x32x16_bf16 v[96:111], v[168:171], v[112:115], v[96:111]
	v_exp_f32_e32 v168, v80
	v_add_f32_e32 v80, 0, v172
	v_add_f32_e32 v80, v173, v80
	v_add_f32_e32 v80, v182, v80
	v_add_f32_e32 v80, v195, v80
	v_add_f32_e32 v80, v196, v80
	v_add_f32_e32 v80, v197, v80
	v_add_f32_e32 v80, v198, v80
	v_add_f32_e32 v80, v199, v80
	v_add_f32_e32 v80, v200, v80
	v_add_f32_e32 v80, v234, v80
	v_add_f32_e32 v80, v235, v80
	v_add_f32_e32 v80, v236, v80
	v_add_f32_e32 v80, v237, v80
	v_exp_f32_e32 v169, v81
	v_add_f32_e32 v80, v238, v80
	v_exp_f32_e32 v170, v82
	v_add_f32_e32 v80, v239, v80
	v_exp_f32_e32 v171, v83
	v_add_f32_e32 v80, v240, v80
	v_mfma_f32_32x32x16_bf16 v[64:79], v[186:189], v[112:115], v[64:79]
	v_exp_f32_e32 v186, v84
	v_add_f32_e32 v80, v168, v80
	v_exp_f32_e32 v187, v85
	v_add_f32_e32 v80, v169, v80
	v_exp_f32_e32 v188, v86
	v_add_f32_e32 v80, v170, v80
	v_exp_f32_e32 v189, v87
	v_add_f32_e32 v80, v171, v80
	v_add_f32_e32 v80, v186, v80
	v_add_f32_e32 v80, v187, v80
	v_add_f32_e32 v80, v188, v80
	v_add_f32_e32 v80, v189, v80
	v_add_f32_e32 v80, v190, v80
	v_add_f32_e32 v80, v191, v80
	v_add_f32_e32 v80, v192, v80
	v_add_f32_e32 v80, v193, v80
	v_add_f32_e32 v80, v241, v80
	v_add_f32_e32 v80, v242, v80
	v_add_f32_e32 v80, v94, v80
	v_add_f32_e32 v80, v95, v80
	v_mov_b32_e32 v81, v80
	v_cvt_pk_bf16_f32 v82, v172, v173
	v_cvt_pk_bf16_f32 v83, v182, v195
	v_cvt_pk_bf16_f32 v84, v196, v197
	s_nop 1
	v_permlane32_swap_b32_e32 v80, v81
	v_cvt_pk_bf16_f32 v85, v198, v199
	v_permlane32_swap_b32_e32 v82, v84
	v_cvt_pk_bf16_f32 v86, v200, v234
	v_cvt_pk_bf16_f32 v87, v235, v236
	v_cvt_pk_bf16_f32 v88, v237, v238
	v_cvt_pk_bf16_f32 v89, v239, v240
	v_cvt_pk_bf16_f32 v90, v168, v169
	v_cvt_pk_bf16_f32 v91, v170, v171
	v_cvt_pk_bf16_f32 v92, v186, v187
	v_cvt_pk_bf16_f32 v93, v188, v189
	v_cvt_pk_bf16_f32 v168, v190, v191
	v_cvt_pk_bf16_f32 v169, v192, v193
	v_cvt_pk_bf16_f32 v170, v241, v242
	v_cvt_pk_bf16_f32 v171, v94, v95
	v_lshl_add_u32 v94, s13, 14, v205
	ds_read_b64_tr_b16 v[186:187], v94 offset:0
	ds_read_b64_tr_b16 v[188:189], v94 offset:0x800
	ds_read_b64_tr_b16 v[190:191], v94 offset:0x1000
	ds_read_b64_tr_b16 v[192:193], v94 offset:0x1800
	ds_read_b64_tr_b16 v[196:197], v94 offset:0x2000
	ds_read_b64_tr_b16 v[198:199], v94 offset:0x2800
	ds_read_b64_tr_b16 v[234:235], v94 offset:0x3000
	ds_read_b64_tr_b16 v[236:237], v94 offset:0x3800
	v_permlane32_swap_b32_e32 v83, v85
	v_permlane32_swap_b32_e32 v86, v88
	v_permlane32_swap_b32_e32 v87, v89
	v_permlane32_swap_b32_e32 v90, v92
	v_permlane32_swap_b32_e32 v91, v93
	v_permlane32_swap_b32_e32 v168, v170
	v_permlane32_swap_b32_e32 v169, v171
	s_setprio 0
	s_waitcnt lgkmcnt(0)
; #define SBAR() __builtin_amdgcn_sched_barrier(0)
; template <bool FIRST>
; __device__ __forceinline__ void partialSM(f32x16& p0, f32x16& p1, float& m_reg, float& mn, float& alpha) {
;     float pmax = p0[0];
; #pragma unroll
;     for (int r = 1; r < 16; ++r) pmax = fmaxf(pmax, p0[r]);
; #pragma unroll
;     for (int r = 0; r < 16; ++r) pmax = fmaxf(pmax, p1[r]);
;     { auto rr = __builtin_amdgcn_permlane32_swap(__float_as_uint(pmax), __float_as_uint(pmax), false, false);
;       pmax = fmaxf(__uint_as_float(rr[0]), __uint_as_float(rr[1])); }
;     if (FIRST) { mn = (fabsf(pmax) <= THRL) ? 0.f : pmax; m_reg = mn; alpha = 1.f; }
;     else if (__builtin_expect(__all(pmax - m_reg <= THRL), 1)) { mn = m_reg; alpha = 1.f; }
;     else { mn = fmaxf(m_reg, pmax); alpha = __builtin_amdgcn_exp2f(m_reg - mn); m_reg = mn; }
; template <int OFF> __device__ __forceinline__ s16x4 tr_read(int vb) {
;     s16x4 r; asm volatile("ds_read_b64_tr_b16 %0, %1 offset:%2" : "=&v"(r) : "v"(vb), "i"(OFF) : "memory"); return r;
; }
; template <int D0> __device__ __forceinline__ void pv_one(f32x16& od, int vb, bf16x8 pa0, bf16x8 pa1, bf16x8 pa2, bf16x8 pa3) {
;     const s16x4 l0 = tr_read<v_rd_off(D0, 0, 0)>(vb), h0 = tr_read<v_rd_off(D0, 0, 1)>(vb), l1 = tr_read<v_rd_off(D0, 1, 0)>(vb), h1 = tr_read<v_rd_off(D0, 1, 1)>(vb);
;     const s16x4 l2 = tr_read<v_rd_off(D0, 2, 0)>(vb), h2 = tr_read<v_rd_off(D0, 2, 1)>(vb), l3 = tr_read<v_rd_off(D0, 3, 0)>(vb), h3 = tr_read<v_rd_off(D0, 3, 1)>(vb);
;     asm volatile("s_waitcnt lgkmcnt(0)" ::: "memory"); SBAR();
;     ...
;     od = __builtin_amdgcn_mfma_f32_32x32x16_bf16(pa0, PK(l0, h0), od, 0, 0, 0);
;     od = __builtin_amdgcn_mfma_f32_32x32x16_bf16(pa1, PK(l1, h1), od, 0, 0, 0);
;     od = __builtin_amdgcn_mfma_f32_32x32x16_bf16(pa2, PK(l2, h2), od, 0, 0, 0);
;     od = __builtin_amdgcn_mfma_f32_32x32x16_bf16(pa3, PK(l3, h3), od, 0, 0, 0);
;     ...
; }
; __device__ __forceinline__ void pv_d0(f32x16* o, int vb, bf16x8 pa0, bf16x8 pa1, bf16x8 pa2, bf16x8 pa3) {
;     pv_one<0>(o[0], vb, pa0, pa1, pa2, pa3); pv_one<1>(o[1], vb, pa0, pa1, pa2, pa3); pv_one<2>(o[2], vb, pa0, pa1, pa2, pa3); pv_one<3>(o[3], vb, pa0, pa1, pa2, pa3);
	s_nop 0
	v_mfma_f32_32x32x16_bf16 v[0:15], v[82:85], v[186:189], v[0:15]
	ds_read_b64_tr_b16 v[186:187], v94 offset:0x200
	ds_read_b64_tr_b16 v[188:189], v94 offset:0xa00
	v_mfma_f32_32x32x16_bf16 v[0:15], v[86:89], v[190:193], v[0:15]
	ds_read_b64_tr_b16 v[190:191], v94 offset:0x1200
	ds_read_b64_tr_b16 v[192:193], v94 offset:0x1a00
	v_mfma_f32_32x32x16_bf16 v[0:15], v[90:93], v[196:199], v[0:15]
	ds_read_b64_tr_b16 v[196:197], v94 offset:0x2200
	ds_read_b64_tr_b16 v[198:199], v94 offset:0x2a00
	v_mfma_f32_32x32x16_bf16 v[0:15], v[168:171], v[234:237], v[0:15]
	ds_read_b64_tr_b16 v[234:235], v94 offset:0x3200
	ds_read_b64_tr_b16 v[236:237], v94 offset:0x3a00
	s_waitcnt lgkmcnt(0)
	v_mfma_f32_32x32x16_bf16 v[48:63], v[82:85], v[186:189], v[48:63]
	ds_read_b64_tr_b16 v[186:187], v94 offset:0x400
	ds_read_b64_tr_b16 v[188:189], v94 offset:0xc00
	v_mfma_f32_32x32x16_bf16 v[48:63], v[86:89], v[190:193], v[48:63]
	ds_read_b64_tr_b16 v[190:191], v94 offset:0x1400
	ds_read_b64_tr_b16 v[192:193], v94 offset:0x1c00
	v_mfma_f32_32x32x16_bf16 v[48:63], v[90:93], v[196:199], v[48:63]
	ds_read_b64_tr_b16 v[196:197], v94 offset:0x2400
	ds_read_b64_tr_b16 v[198:199], v94 offset:0x2c00
	v_mfma_f32_32x32x16_bf16 v[48:63], v[168:171], v[234:237], v[48:63]
	ds_read_b64_tr_b16 v[234:235], v94 offset:0x3400
	ds_read_b64_tr_b16 v[236:237], v94 offset:0x3c00
	s_waitcnt lgkmcnt(0)
	v_mfma_f32_32x32x16_bf16 v[32:47], v[82:85], v[186:189], v[32:47]
	ds_read_b64_tr_b16 v[186:187], v94 offset:0x600
	ds_read_b64_tr_b16 v[188:189], v94 offset:0xe00
	v_mfma_f32_32x32x16_bf16 v[32:47], v[86:89], v[190:193], v[32:47]
	ds_read_b64_tr_b16 v[190:191], v94 offset:0x1600
	ds_read_b64_tr_b16 v[192:193], v94 offset:0x1e00
	v_mfma_f32_32x32x16_bf16 v[32:47], v[90:93], v[196:199], v[32:47]
	ds_read_b64_tr_b16 v[196:197], v94 offset:0x2600
	ds_read_b64_tr_b16 v[198:199], v94 offset:0x2e00
	v_mfma_f32_32x32x16_bf16 v[32:47], v[168:171], v[234:237], v[32:47]
	ds_read_b64_tr_b16 v[234:235], v94 offset:0x3600
	ds_read_b64_tr_b16 v[236:237], v94 offset:0x3e00
	s_waitcnt lgkmcnt(0)
	v_mfma_f32_32x32x16_bf16 v[16:31], v[82:85], v[186:189], v[16:31]
	v_max_f32_e32 v82, v97, v97
	v_max_f32_e32 v83, v96, v96
	v_max_f32_e32 v82, v83, v82
	v_max3_f32 v82, v82, v98, v99
	v_max3_f32 v82, v82, v100, v101
	v_max3_f32 v82, v82, v102, v103
	v_max3_f32 v82, v82, v104, v105
	v_mfma_f32_32x32x16_bf16 v[16:31], v[86:89], v[190:193], v[16:31]
	v_max3_f32 v82, v82, v106, v107
	v_max3_f32 v82, v82, v108, v109
	v_max3_f32 v82, v82, v110, v111
	v_max3_f32 v82, v82, v64, v65
	v_max3_f32 v82, v82, v66, v67
	v_max3_f32 v82, v82, v68, v69
	v_max3_f32 v82, v82, v70, v71
	v_mfma_f32_32x32x16_bf16 v[16:31], v[90:93], v[196:199], v[16:31]
	v_max3_f32 v82, v82, v72, v73
	v_max3_f32 v82, v82, v74, v75
	v_max3_f32 v82, v82, v76, v77
	v_max3_f32 v82, v82, v78, v79
	v_mov_b32_e32 v83, v82
	s_nop 1
	v_permlane32_swap_b32_e32 v82, v83
	v_max_f32_e32 v83, v83, v83
	v_max_f32_e32 v82, v82, v82
	v_mfma_f32_32x32x16_bf16 v[16:31], v[168:171], v[234:237], v[16:31]
	v_max_f32_e32 v82, v82, v83
	v_sub_f32_e32 v83, v82, v184
	v_cmp_ge_f32_e32 vcc, 0x41300000, v83
	v_mov_b32_e32 v182, v184
	s_cmp_eq_u64 vcc, exec
	s_cbranch_scc0 .Latt_slow2
	s_cmp_lg_u32 s19, 0
	s_cbranch_scc0 .LBB0_229
	v_mov_b32_e32 v184, 1.0
